# speedup vs baseline: 1.0055x; 1.0053x over previous
; __device__ __forceinline__ void scan_pc(const Params& p, int j, const u16* R, const u16* K, const u16* V, u16* Y, u16* YB) {
;     ...
;     auto load_raw = [&](int c, Raw& q_) {
;       unsigned offA = (unsigned)(offA0 + c * dA);
;       _Pragma("unroll") for (int ks = 0; ks < 2; ++ks) { q_.rw[ks] = ldo<bf16x8>(wmid, offA + ks * 64); q_.ra[ks] = ldo<bf16x8>(amid, offA + ks * 64); }
;       _Pragma("unroll") for (int jj = 0; jj < 4; ++jj) {
;         unsigned off = (unsigned)(offK0[jj] + c * dK);
;         q_.rk[jj] = ldo<u16>(K, off); q_.rr[jj] = ldo<u16>(R, off); q_.rv[jj] = ldo<u16>(V, off);
;       }
;     };
;     ...
;         load_raw(min(c + 4, nch - 1), rn);
.LBB0_2718:
	s_or_b64 exec, exec, s[30:31]
	s_waitcnt vmcnt(28)
	v_add_u32_e32 v0, 5, v90
	v_min_i32_e32 v6, s29, v0
	v_mad_u64_u32 v[4:5], s[30:31], v6, s9, v[80:81]
	global_load_dwordx4 v[8:11], v4, s[72:73]
	global_load_dwordx4 v[0:3], v4, s[72:73] offset:64
	s_nop 0
	global_load_dwordx4 v[12:15], v4, s[60:61]
	s_nop 0
	global_load_dwordx4 v[4:7], v4, s[60:61] offset:64
	s_mov_b32 s30, 0x5040100

; __device__ __forceinline__ void scan_pc(const Params& p, int j, const u16* R, const u16* K, const u16* V, u16* Y, u16* YB) {
;     ...
;     auto load_raw = [&](int c, Raw& q_) {
;       unsigned offA = (unsigned)(offA0 + c * dA);
;       _Pragma("unroll") for (int ks = 0; ks < 2; ++ks) { q_.rw[ks] = ldo<bf16x8>(wmid, offA + ks * 64); q_.ra[ks] = ldo<bf16x8>(amid, offA + ks * 64); }
;       _Pragma("unroll") for (int jj = 0; jj < 4; ++jj) {
;         unsigned off = (unsigned)(offK0[jj] + c * dK);
;         q_.rk[jj] = ldo<u16>(K, off); q_.rr[jj] = ldo<u16>(R, off); q_.rv[jj] = ldo<u16>(V, off);
;       }
;     };
;     auto load_yold = [&](int c) {
;       _Pragma("unroll") for (int jj = 0; jj < 4; ++jj) yo[jj] = b2f(ldo<u16>(Yw, (unsigned)(offK0[jj] + c * dK)));
;     };
;     auto stage_a = [&](int c, const Raw& q_) {
;       u16* IMG = shm + (c % 3) * IMG_ELEMS;
;       f32x4 cw = {0.f, 0.f, 0.f, 0.f}, ca = {0.f, 0.f, 0.f, 0.f};
;       _Pragma("unroll") for (int ks = 0; ks < 2; ++ks) { cw = MFMA16(q_.rw[ks], LB[ks * 64], cw); ca = MFMA16(q_.ra[ks], LB[(2 + ks) * 64], ca); }
;       float kv[4], kk[4], ic[4], lw[4];
;       _Pragma("unroll") for (int jj = 0; jj < 4; ++jj) {
;         kv[jj] = b2f(q_.rk[jj]);
;         kk[jj] = kv[jj] * kkme;
;         float ss = row_sum(kk[jj] * kk[jj]);
;         reinterpret_cast<float*>(IMG + IMG_PL)[128 + w4 * 16 + fq * 4 + jj] = ss;
;         lw[jj] = -0.8750360036f * sigmoidf_(w0c + cw[jj]);
;         ic[jj] = sigmoidf_(a0c + ca[jj]);
;       }
;       s4 lhi = pack4(lw[0], lw[1], lw[2], lw[3]);
;       s4 llo = pack4(lw[0] - b2f((u16)lhi[0]), lw[1] - b2f((u16)lhi[1]), lw[2] - b2f((u16)lhi[2]), lw[3] - b2f((u16)lhi[3]));
;       f32x4 cum = {0.f, 0.f, 0.f, 0.f};
;       cum = MFMA4(ltri, lhi, cum);
;       cum = MFMA4(ltri, llo, cum);
;       float bt[4], kt[4], ep3 = 0.f;
;       _Pragma("unroll") for (int jj = 0; jj < 4; ++jj) {
;         float ep = __builtin_amdgcn_exp2f(cum[jj]), em = __builtin_amdgcn_exp2f(-cum[jj]), ex = __builtin_amdgcn_exp2f(cum[jj] - lw[jj]);
;         float at = -kk[jj] * ex;
;         float rraw = b2f(q_.rr[jj]);
;         float rt = rraw * ep;
;         float kd = kv[jj] * (1.f + (ic[jj] - 1.f) * kac);
;         bt[jj] = kk[jj] * ic[jj] * em;
;         kt[jj] = kd * em;
;         int t = fq * 4 + jj, kc = w4 * 16 + fr;
;         float bsum = row_sum(rraw * kd * rkc);
.LBB0_2739:
	s_or_saveexec_b64 s[26:27], s[26:27]
	s_mul_hi_u32 s30, s3, 0xaaaaaaab
	s_lshr_b32 s30, s30, 1
	s_mul_i32 s30, s30, 3
	s_sub_i32 s76, 2, s30
	v_add_u32_e32 v94, 2, v90
	s_xor_b64 exec, exec, s[26:27]
	s_cbranch_execz .LBB0_2745
	s_waitcnt vmcnt(16)
	v_lshl_or_b32 v161, v207, 16, v206
	v_lshl_or_b32 v159, v209, 16, v208
	v_lshl_or_b32 v160, v211, 16, v210
	v_lshl_or_b32 v158, v213, 16, v212
	v_lshl_or_b32 v82, v215, 16, v214
	v_lshl_or_b32 v83, v217, 16, v216
	v_add_u32_e32 v50, 4, v90
	v_min_i32_e32 v50, s29, v50
	v_mul_lo_u32 v50, v50, s8
	v_add_u32_e32 v51, v50, v154
	v_add_u32_e32 v54, v50, v155
	v_add_u32_e32 v55, v50, v156
	v_add_u32_e32 v50, v50, v157
	global_load_ushort v208, v55, s[58:59]
	global_load_ushort v209, v50, s[58:59]
	global_load_ushort v206, v51, s[58:59]
	global_load_ushort v210, v51, s[54:55]
	global_load_ushort v207, v54, s[58:59]
	global_load_ushort v211, v54, s[54:55]
	global_load_ushort v212, v55, s[54:55]
	global_load_ushort v216, v55, s[4:5]
	global_load_ushort v215, v54, s[4:5]
	global_load_ushort v214, v51, s[4:5]
	global_load_ushort v213, v50, s[54:55]
	global_load_ushort v217, v50, s[4:5]
	v_add_u32_e32 v50, 2, v90
	v_cmp_gt_u32_e32 vcc, s2, v50
	s_and_saveexec_b64 s[30:31], vcc
	s_cbranch_execz .LBB0_2744
	ds_read_b128 v[58:61], v111
	ds_read_b128 v[234:237], v111 offset:2048
	ds_read_b128 v[238:241], v111 offset:1024
	ds_read_b128 v[242:245], v111 offset:3072
	s_mov_b32 s62, 0xbf60025c
	v_add_u32_e32 v50, s76, v90
	s_waitcnt lgkmcnt(3)
	v_mfma_f32_16x16x32_bf16 v[20:23], v[20:23], v[58:61], 0
	s_waitcnt lgkmcnt(2)
	v_mfma_f32_16x16x32_bf16 v[28:31], v[28:31], v[234:237], 0
	s_waitcnt lgkmcnt(1)
	v_mfma_f32_16x16x32_bf16 v[16:19], v[16:19], v[238:241], v[20:23]
	s_waitcnt lgkmcnt(0)
	v_mfma_f32_16x16x32_bf16 v[20:23], v[24:27], v[242:245], v[28:31]
	s_nop 5
	v_add_f32_e32 v16, v152, v16
	v_add_f32_e32 v17, v152, v17
	v_mul_f32_e32 v16, 0xbfb8aa3b, v16
	s_nop 2
	v_add_f32_e32 v20, v153, v20
	v_mul_f32_e32 v20, 0xbfb8aa3b, v20
	v_exp_f32_e32 v20, v20
	v_mul_f32_e32 v17, 0xbfb8aa3b, v17
	v_add_f32_e32 v18, v152, v18
	v_add_f32_e32 v19, v152, v19
	v_add_f32_e32 v20, 1.0, v20
	v_rcp_f32_e32 v26, v20
	v_add_f32_e32 v20, v153, v21
	v_mul_f32_e32 v20, 0xbfb8aa3b, v20
	v_exp_f32_e32 v20, v20
	v_exp_f32_e32 v16, v16
	v_exp_f32_e32 v17, v17
	v_mul_f32_e32 v18, 0xbfb8aa3b, v18
	v_add_f32_e32 v20, 1.0, v20
	v_rcp_f32_e32 v27, v20
	v_add_f32_e32 v20, v153, v22
	v_mul_f32_e32 v20, 0xbfb8aa3b, v20
	v_exp_f32_e32 v20, v20
	v_mul_f32_e32 v19, 0xbfb8aa3b, v19
	v_exp_f32_e32 v18, v18
	v_exp_f32_e32 v19, v19
	v_add_f32_e32 v20, 1.0, v20
	v_rcp_f32_e32 v22, v20
	v_add_f32_e32 v20, v153, v23
	v_add_f32_e32 v16, 1.0, v16
	v_add_f32_e32 v17, 1.0, v17
	v_mul_f32_e32 v20, 0xbfb8aa3b, v20
	v_rcp_f32_e32 v16, v16
	v_rcp_f32_e32 v17, v17
	v_add_f32_e32 v18, 1.0, v18
	v_add_f32_e32 v19, 1.0, v19
	v_exp_f32_e32 v20, v20
	v_rcp_f32_e32 v18, v18
	v_rcp_f32_e32 v19, v19
	v_pk_mul_f32 v[28:29], v[16:17], s[62:63] op_sel_hi:[1,0]
	v_add_f32_e32 v20, 1.0, v20
	v_rcp_f32_e32 v23, v20
	v_pk_mul_f32 v[30:31], v[18:19], s[62:63] op_sel_hi:[1,0]
	v_cvt_pk_bf16_f32 v20, v28, v29
	v_mad_u32_u24 v24, v50, s80, 0
	v_cvt_pk_bf16_f32 v21, v30, v31
	v_and_b32_e32 v51, 0xffff0000, v20
	v_lshlrev_b32_e32 v50, 16, v20
	v_pk_fma_f32 v[16:17], v[16:17], s[62:63], v[50:51] op_sel_hi:[1,0,1] neg_lo:[0,0,1] neg_hi:[0,0,1]
	v_and_b32_e32 v51, 0xffff0000, v21
	v_lshlrev_b32_e32 v50, 16, v21
	v_pk_fma_f32 v[18:19], v[18:19], s[62:63], v[50:51] op_sel_hi:[1,0,1] neg_lo:[0,0,1] neg_hi:[0,0,1]
	v_cvt_pk_bf16_f32 v50, v16, v17
	v_cvt_pk_bf16_f32 v51, v18, v19
	v_mfma_f32_16x16x16_bf16 v[16:19], v[72:73], v[20:21], 0
	v_add_u32_e32 v60, v24, v115
	v_add_u32_e32 v61, v60, v117
	v_add3_u32 v66, v24, v117, v115
	v_mfma_f32_16x16x16_bf16 v[18:21], v[72:73], v[50:51], v[16:19]
	v_add_u32_e32 v25, v24, v113
	v_add_u32_e32 v62, v25, v112
	v_lshl_add_u32 v63, v97, 2, v25
	s_nop 4
	v_sub_f32_e32 v16, v18, v28
	v_exp_f32_e32 v58, v18
	v_exp_f32_e64 v50, -v18
	v_exp_f32_e32 v59, v16
	v_exp_f32_e32 v67, v19
	v_exp_f32_e64 v51, -v19
	v_sub_f32_e32 v16, v19, v29
	v_and_b32_e32 v19, 0xffff0000, v161
	v_lshlrev_b32_e32 v18, 16, v161
	v_pk_mul_f32 v[54:55], v[76:77], v[18:19]
	v_exp_f32_e32 v68, v16
	v_pk_mul_f32 v[16:17], v[54:55], v[54:55]
	s_nop 1
	v_mov_b32_dpp v16, v16 quad_perm:[1,0,3,2] row_mask:0xf bank_mask:0xf bound_ctrl:1
	v_mov_b32_dpp v17, v17 quad_perm:[1,0,3,2] row_mask:0xf bank_mask:0xf bound_ctrl:1
	v_pk_fma_f32 v[16:17], v[54:55], v[54:55], v[16:17]
	s_nop 1
	v_mov_b32_dpp v28, v16 quad_perm:[2,3,0,1] row_mask:0xf bank_mask:0xf bound_ctrl:1
	v_mov_b32_dpp v29, v17 quad_perm:[2,3,0,1] row_mask:0xf bank_mask:0xf bound_ctrl:1
	v_pk_add_f32 v[16:17], v[16:17], v[28:29]
	s_nop 1
	v_mov_b32_dpp v28, v16 row_half_mirror row_mask:0xf bank_mask:0xf bound_ctrl:1
	v_mov_b32_dpp v29, v17 row_half_mirror row_mask:0xf bank_mask:0xf bound_ctrl:1
	v_pk_add_f32 v[16:17], v[16:17], v[28:29]
	s_nop 1
	v_mov_b32_dpp v28, v16 row_ror:8 row_mask:0xf bank_mask:0xf bound_ctrl:1
	v_mov_b32_dpp v29, v17 row_ror:8 row_mask:0xf bank_mask:0xf bound_ctrl:1
	v_pk_add_f32 v[28:29], v[16:17], v[28:29]
	v_mul_f32_e64 v16, v59, -v54
	v_cvt_pk_bf16_f32 v16, v16, s0
	ds_write_b16 v61, v16
	v_pk_mul_f32 v[16:17], v[54:55], v[26:27]
	v_pk_add_f32 v[26:27], v[26:27], -1.0 op_sel_hi:[1,0]
	v_pk_mul_f32 v[16:17], v[16:17], v[50:51]
	v_pk_fma_f32 v[26:27], v[74:75], v[26:27], 1.0 op_sel_hi:[1,1,0]
	v_cvt_pk_bf16_f32 v54, v16, s0
	v_pk_mul_f32 v[26:27], v[26:27], v[18:19]
	ds_write_b16 v66, v54 offset:4608
	v_pk_mul_f32 v[18:19], v[26:27], v[50:51]
	v_mul_f32_e64 v54, v68, -v55
; __device__ __forceinline__ float b2f(u16 b) { return __uint_as_float(((unsigned)b) << 16); }
; __device__ __forceinline__ void scan_pc(const Params& p, int j, const u16* R, const u16* K, const u16* V, u16* Y, u16* YB) {
;     ...
;     auto load_raw = [&](int c, Raw& q_) {
;       unsigned offA = (unsigned)(offA0 + c * dA);
;       _Pragma("unroll") for (int ks = 0; ks < 2; ++ks) { q_.rw[ks] = ldo<bf16x8>(wmid, offA + ks * 64); q_.ra[ks] = ldo<bf16x8>(amid, offA + ks * 64); }
;       _Pragma("unroll") for (int jj = 0; jj < 4; ++jj) {
;         unsigned off = (unsigned)(offK0[jj] + c * dK);
;         q_.rk[jj] = ldo<u16>(K, off); q_.rr[jj] = ldo<u16>(R, off); q_.rv[jj] = ldo<u16>(V, off);
;       }
;     };
;     ...
;       _Pragma("unroll") for (int jj = 0; jj < 4; ++jj) {
;         float ep = __builtin_amdgcn_exp2f(cum[jj]), em = __builtin_amdgcn_exp2f(-cum[jj]), ex = __builtin_amdgcn_exp2f(cum[jj] - lw[jj]);
;         float at = -kk[jj] * ex;
;         float rraw = b2f(q_.rr[jj]);
;         float rt = rraw * ep;
;         float kd = kv[jj] * (1.f + (ic[jj] - 1.f) * kac);
;         bt[jj] = kk[jj] * ic[jj] * em;
;         kt[jj] = kd * em;
;         int t = fq * 4 + jj, kc = w4 * 16 + fr;
;         float bsum = row_sum(rraw * kd * rkc);
;         reinterpret_cast<float*>(IMG + IMG_PL)[64 + w4 * 16 + t] = bsum;
;         IMG[(0 * 16 + t) * XT_LD + kc] = f2b(at);
;         IMG[(1 * 16 + t) * XT_LD + kc] = f2b(rt);
;         IMG[(2 * 16 + t) * XT_LD + kc] = f2b(bt[jj]);
;         IMG[(3 * 16 + t) * XT_LD + kc] = f2b(kt[jj]);
;         if (jj == 3) ep3 = ep;
;       }
;       if (fq == 3) reinterpret_cast<float*>(IMG + IMG_PL)[w4 * 16 + fr] = ep3;
;       *reinterpret_cast<s4*>(IMG + IMG_XK + (0 * 64 + w4 * 16 + fr) * XK_LD + fq * 4) = pack4(bt[0], bt[1], bt[2], bt[3]);
;       *reinterpret_cast<s4*>(IMG + IMG_XK + (1 * 64 + w4 * 16 + fr) * XK_LD + fq * 4) = pack4(kt[0], kt[1], kt[2], kt[3]);
;       s4 vp; _Pragma("unroll") for (int jj = 0; jj < 4; ++jj) vp[jj] = (short)q_.rv[jj];
;       *reinterpret_cast<s4*>(IMG + IMG_VT + (w4 * 16 + fr) * XK_LD + fq * 4) = vp;
	v_cvt_pk_bf16_f32 v50, v18, s0
	ds_write_b16 v66, v50 offset:6912
	v_lshlrev_b32_e32 v50, 16, v160
	v_and_b32_e32 v51, 0xffff0000, v160
	v_mul_f32_e32 v55, v58, v50
	v_cvt_pk_bf16_f32 v55, v55, s0
	v_pk_mul_f32 v[26:27], v[26:27], v[50:51]
	ds_write_b16 v66, v55 offset:2304
	v_mul_f32_e32 v55, v67, v51
	v_pk_mul_f32 v[50:51], v[78:79], v[26:27]
	v_exp_f32_e32 v66, v20
	s_nop 0
	v_mov_b32_dpp v50, v50 quad_perm:[1,0,3,2] row_mask:0xf bank_mask:0xf bound_ctrl:1
	v_mov_b32_dpp v51, v51 quad_perm:[1,0,3,2] row_mask:0xf bank_mask:0xf bound_ctrl:1
	v_pk_fma_f32 v[26:27], v[78:79], v[26:27], v[50:51]
	s_nop 1
	v_mov_b32_dpp v50, v26 quad_perm:[2,3,0,1] row_mask:0xf bank_mask:0xf bound_ctrl:1
	v_mov_b32_dpp v51, v27 quad_perm:[2,3,0,1] row_mask:0xf bank_mask:0xf bound_ctrl:1
	v_pk_add_f32 v[26:27], v[26:27], v[50:51]
	s_nop 1
	v_mov_b32_dpp v50, v26 row_half_mirror row_mask:0xf bank_mask:0xf bound_ctrl:1
	v_mov_b32_dpp v51, v27 row_half_mirror row_mask:0xf bank_mask:0xf bound_ctrl:1
	v_pk_add_f32 v[26:27], v[26:27], v[50:51]
	s_nop 1
	v_mov_b32_dpp v50, v26 row_ror:8 row_mask:0xf bank_mask:0xf bound_ctrl:1
	v_mov_b32_dpp v51, v27 row_ror:8 row_mask:0xf bank_mask:0xf bound_ctrl:1
	v_pk_add_f32 v[58:59], v[26:27], v[50:51]
	v_cvt_pk_bf16_f32 v26, v54, s0
	v_add_u32_e32 v27, v60, v120
	ds_write_b16 v27, v26
	v_cvt_pk_bf16_f32 v26, v55, s0
	v_add3_u32 v27, v24, v120, v115
	ds_write_b16 v27, v26 offset:2304
	v_cvt_pk_bf16_f32 v26, v17, s0
	v_exp_f32_e64 v50, -v20
	v_sub_f32_e32 v20, v20, v30
	v_and_b32_e32 v55, 0xffff0000, v159
	v_lshlrev_b32_e32 v54, 16, v159
	ds_write_b16 v27, v26 offset:4608
	v_cvt_pk_bf16_f32 v26, v19, s0
	v_exp_f32_e32 v67, v20
	v_sub_f32_e32 v20, v21, v31
	v_pk_mul_f32 v[60:61], v[76:77], v[54:55]
	ds_write_b16 v27, v26 offset:6912
	v_exp_f32_e32 v26, v21
	v_exp_f32_e64 v51, -v21
	v_exp_f32_e32 v68, v20
	v_pk_mul_f32 v[20:21], v[60:61], v[60:61]
	s_nop 1
	v_mov_b32_dpp v20, v20 quad_perm:[1,0,3,2] row_mask:0xf bank_mask:0xf bound_ctrl:1
	v_mov_b32_dpp v21, v21 quad_perm:[1,0,3,2] row_mask:0xf bank_mask:0xf bound_ctrl:1
	v_pk_fma_f32 v[20:21], v[60:61], v[60:61], v[20:21]
	s_nop 1
	v_mov_b32_dpp v30, v20 quad_perm:[2,3,0,1] row_mask:0xf bank_mask:0xf bound_ctrl:1
	v_mov_b32_dpp v31, v21 quad_perm:[2,3,0,1] row_mask:0xf bank_mask:0xf bound_ctrl:1
	v_pk_add_f32 v[20:21], v[20:21], v[30:31]
	s_nop 1
	v_mov_b32_dpp v30, v20 row_half_mirror row_mask:0xf bank_mask:0xf bound_ctrl:1
	v_mov_b32_dpp v31, v21 row_half_mirror row_mask:0xf bank_mask:0xf bound_ctrl:1
	v_pk_add_f32 v[20:21], v[20:21], v[30:31]
	s_nop 1
	v_mov_b32_dpp v30, v20 row_ror:8 row_mask:0xf bank_mask:0xf bound_ctrl:1
	v_mov_b32_dpp v31, v21 row_ror:8 row_mask:0xf bank_mask:0xf bound_ctrl:1
	v_pk_add_f32 v[30:31], v[20:21], v[30:31]
	v_mul_f32_e64 v20, v67, -v60
	v_cvt_pk_bf16_f32 v20, v20, s0
	ds_write_b16 v27, v20 offset:144
	v_pk_mul_f32 v[20:21], v[60:61], v[22:23]
	v_pk_add_f32 v[22:23], v[22:23], -1.0 op_sel_hi:[1,0]
	v_pk_mul_f32 v[20:21], v[20:21], v[50:51]
	ds_write_b128 v62, v[28:31] offset:17408
	v_cvt_pk_bf16_f32 v28, v20, s0
	v_pk_fma_f32 v[22:23], v[74:75], v[22:23], 1.0 op_sel_hi:[1,1,0]
	ds_write_b16 v27, v28 offset:4752
	v_pk_mul_f32 v[28:29], v[22:23], v[54:55]
	v_and_b32_e32 v31, 0xffff0000, v158
	v_pk_mul_f32 v[22:23], v[28:29], v[50:51]
	v_mul_f32_e64 v62, v68, -v61
	v_cvt_pk_bf16_f32 v30, v22, s0
	ds_write_b16 v27, v30 offset:7056
	v_lshlrev_b32_e32 v30, 16, v158
	v_mul_f32_e32 v50, v66, v30
	v_cvt_pk_bf16_f32 v50, v50, s0
	v_pk_mul_f32 v[28:29], v[28:29], v[30:31]
	ds_write_b16 v27, v50 offset:2448
	v_mul_f32_e32 v50, v26, v31
	v_pk_mul_f32 v[30:31], v[78:79], v[28:29]
	s_nop 1
	v_mov_b32_dpp v30, v30 quad_perm:[1,0,3,2] row_mask:0xf bank_mask:0xf bound_ctrl:1
	v_mov_b32_dpp v31, v31 quad_perm:[1,0,3,2] row_mask:0xf bank_mask:0xf bound_ctrl:1
	v_pk_fma_f32 v[28:29], v[78:79], v[28:29], v[30:31]
	s_nop 1
	v_mov_b32_dpp v30, v28 quad_perm:[2,3,0,1] row_mask:0xf bank_mask:0xf bound_ctrl:1
	v_mov_b32_dpp v31, v29 quad_perm:[2,3,0,1] row_mask:0xf bank_mask:0xf bound_ctrl:1
	v_pk_add_f32 v[28:29], v[28:29], v[30:31]
	s_nop 1
	v_mov_b32_dpp v30, v28 row_half_mirror row_mask:0xf bank_mask:0xf bound_ctrl:1
	v_mov_b32_dpp v31, v29 row_half_mirror row_mask:0xf bank_mask:0xf bound_ctrl:1
	v_pk_add_f32 v[28:29], v[28:29], v[30:31]
	s_nop 1
	v_mov_b32_dpp v30, v28 row_ror:8 row_mask:0xf bank_mask:0xf bound_ctrl:1
	v_mov_b32_dpp v31, v29 row_ror:8 row_mask:0xf bank_mask:0xf bound_ctrl:1
	v_pk_add_f32 v[60:61], v[28:29], v[30:31]
	v_cvt_pk_bf16_f32 v28, v62, s0
	ds_write_b16 v27, v28 offset:288
	v_cvt_pk_bf16_f32 v28, v50, s0
	ds_write_b16 v27, v28 offset:2592
	v_cvt_pk_bf16_f32 v28, v21, s0
	ds_write_b16 v27, v28 offset:4896
	v_cvt_pk_bf16_f32 v28, v23, s0
	ds_write_b128 v63, v[58:61] offset:17152
	ds_write_b16 v27, v28 offset:7200
	s_and_saveexec_b64 s[62:63], s[12:13]
	v_lshl_add_u32 v25, v96, 2, v25
	ds_write_b32 v25, v26 offset:16896
	s_or_b64 exec, exec, s[62:63]
	v_cvt_pk_bf16_f32 v16, v16, v17
	v_cvt_pk_bf16_f32 v17, v20, v21
	v_add3_u32 v20, v24, v127, v133
	v_cvt_pk_bf16_f32 v18, v18, v19
	v_cvt_pk_bf16_f32 v19, v22, v23
	ds_write2st64_b64 v20, v[16:17], v[18:19] offset0:18 offset1:23
	ds_write_b64 v20, v[82:83] offset:14336
.LBB0_2744:
	s_or_b64 exec, exec, s[30:31]
	s_waitcnt vmcnt(28)
	v_add_u32_e32 v16, 4, v90
	v_min_i32_e32 v26, s29, v16
	v_mad_u64_u32 v[24:25], s[30:31], v26, s9, v[80:81]
	global_load_dwordx4 v[20:23], v24, s[72:73]
	global_load_dwordx4 v[16:19], v24, s[72:73] offset:64
	s_nop 0
	global_load_dwordx4 v[28:31], v24, s[60:61]
	s_nop 0
	global_load_dwordx4 v[24:27], v24, s[60:61] offset:64
	s_mov_b32 s30, 0x5040100

; __device__ __forceinline__ void scan_pc(const Params& p, int j, const u16* R, const u16* K, const u16* V, u16* Y, u16* YB) {
;     ...
;     auto load_raw = [&](int c, Raw& q_) {
;       unsigned offA = (unsigned)(offA0 + c * dA);
;       _Pragma("unroll") for (int ks = 0; ks < 2; ++ks) { q_.rw[ks] = ldo<bf16x8>(wmid, offA + ks * 64); q_.ra[ks] = ldo<bf16x8>(amid, offA + ks * 64); }
;       _Pragma("unroll") for (int jj = 0; jj < 4; ++jj) {
;         unsigned off = (unsigned)(offK0[jj] + c * dK);
;         q_.rk[jj] = ldo<u16>(K, off); q_.rr[jj] = ldo<u16>(R, off); q_.rv[jj] = ldo<u16>(V, off);
;       }
;     };
;     auto load_yold = [&](int c) {
;       _Pragma("unroll") for (int jj = 0; jj < 4; ++jj) yo[jj] = b2f(ldo<u16>(Yw, (unsigned)(offK0[jj] + c * dK)));
;     };
;     auto stage_a = [&](int c, const Raw& q_) {
;       u16* IMG = shm + (c % 3) * IMG_ELEMS;
;       f32x4 cw = {0.f, 0.f, 0.f, 0.f}, ca = {0.f, 0.f, 0.f, 0.f};
;       _Pragma("unroll") for (int ks = 0; ks < 2; ++ks) { cw = MFMA16(q_.rw[ks], LB[ks * 64], cw); ca = MFMA16(q_.ra[ks], LB[(2 + ks) * 64], ca); }
;       float kv[4], kk[4], ic[4], lw[4];
;       _Pragma("unroll") for (int jj = 0; jj < 4; ++jj) {
;         kv[jj] = b2f(q_.rk[jj]);
;         kk[jj] = kv[jj] * kkme;
;         float ss = row_sum(kk[jj] * kk[jj]);
;         reinterpret_cast<float*>(IMG + IMG_PL)[128 + w4 * 16 + fq * 4 + jj] = ss;
;         lw[jj] = -0.8750360036f * sigmoidf_(w0c + cw[jj]);
;         ic[jj] = sigmoidf_(a0c + ca[jj]);
;       }
;       s4 lhi = pack4(lw[0], lw[1], lw[2], lw[3]);
;       s4 llo = pack4(lw[0] - b2f((u16)lhi[0]), lw[1] - b2f((u16)lhi[1]), lw[2] - b2f((u16)lhi[2]), lw[3] - b2f((u16)lhi[3]));
;       f32x4 cum = {0.f, 0.f, 0.f, 0.f};
;       cum = MFMA4(ltri, lhi, cum);
;       cum = MFMA4(ltri, llo, cum);
;       float bt[4], kt[4], ep3 = 0.f;
;       _Pragma("unroll") for (int jj = 0; jj < 4; ++jj) {
;         float ep = __builtin_amdgcn_exp2f(cum[jj]), em = __builtin_amdgcn_exp2f(-cum[jj]), ex = __builtin_amdgcn_exp2f(cum[jj] - lw[jj]);
;         float at = -kk[jj] * ex;
;         float rraw = b2f(q_.rr[jj]);
;         float rt = rraw * ep;
;         float kd = kv[jj] * (1.f + (ic[jj] - 1.f) * kac);
;         bt[jj] = kk[jj] * ic[jj] * em;
;         kt[jj] = kd * em;
;         int t = fq * 4 + jj, kc = w4 * 16 + fr;
;         float bsum = row_sum(rraw * kd * rkc);
.LBB0_2764:
	s_andn2_saveexec_b64 s[26:27], s[26:27]
	s_cbranch_execz .LBB0_2719
	s_waitcnt vmcnt(16)
	v_lshl_or_b32 v165, v219, 16, v218
	v_lshl_or_b32 v163, v221, 16, v220
	v_lshl_or_b32 v164, v223, 16, v222
	v_lshl_or_b32 v162, v225, 16, v224
	v_lshl_or_b32 v84, v227, 16, v226
	v_lshl_or_b32 v85, v229, 16, v228
	v_add_u32_e32 v50, 5, v90
	v_min_i32_e32 v50, s29, v50
	v_mul_lo_u32 v50, v50, s8
	v_add_u32_e32 v51, v50, v154
	v_add_u32_e32 v54, v50, v155
	v_add_u32_e32 v55, v50, v156
	v_add_u32_e32 v50, v50, v157
	global_load_ushort v220, v55, s[58:59]
	global_load_ushort v221, v50, s[58:59]
	global_load_ushort v218, v51, s[58:59]
	global_load_ushort v222, v51, s[54:55]
	global_load_ushort v219, v54, s[58:59]
	global_load_ushort v223, v54, s[54:55]
	global_load_ushort v224, v55, s[54:55]
	global_load_ushort v228, v55, s[4:5]
	global_load_ushort v227, v54, s[4:5]
	global_load_ushort v226, v51, s[4:5]
	global_load_ushort v225, v50, s[54:55]
	global_load_ushort v229, v50, s[4:5]
	v_add_u32_e32 v50, 3, v90
	v_cmp_gt_u32_e32 vcc, s2, v50
	s_and_saveexec_b64 s[30:31], vcc
	s_cbranch_execz .LBB0_2718
	ds_read_b128 v[58:61], v111
	ds_read_b128 v[234:237], v111 offset:2048
	ds_read_b128 v[238:241], v111 offset:1024
	ds_read_b128 v[242:245], v111 offset:3072
	s_mul_hi_u32 s62, s65, 0xaaaaaaab
	s_lshr_b32 s62, s62, 1
	s_mul_i32 s62, s62, 3
	v_subrev_u32_e32 v50, s62, v90
	s_waitcnt lgkmcnt(3)
	v_mfma_f32_16x16x32_bf16 v[8:11], v[8:11], v[58:61], 0
	s_mov_b32 s62, 0xbf60025c
	v_add_u32_e32 v50, 3, v50
	s_waitcnt lgkmcnt(2)
	v_mfma_f32_16x16x32_bf16 v[12:15], v[12:15], v[234:237], 0
	s_waitcnt lgkmcnt(1)
	v_mfma_f32_16x16x32_bf16 v[0:3], v[0:3], v[238:241], v[8:11]
	s_waitcnt lgkmcnt(0)
	v_mfma_f32_16x16x32_bf16 v[4:7], v[4:7], v[242:245], v[12:15]
	s_nop 5
	v_add_f32_e32 v0, v152, v0
	v_add_f32_e32 v1, v152, v1
	v_mul_f32_e32 v0, 0xbfb8aa3b, v0
	s_nop 2
	v_add_f32_e32 v4, v153, v4
	v_mul_f32_e32 v4, 0xbfb8aa3b, v4
	v_exp_f32_e32 v4, v4
	v_mul_f32_e32 v1, 0xbfb8aa3b, v1
	v_add_f32_e32 v2, v152, v2
	v_add_f32_e32 v3, v152, v3
	v_add_f32_e32 v4, 1.0, v4
	v_rcp_f32_e32 v10, v4
	v_add_f32_e32 v4, v153, v5
	v_mul_f32_e32 v4, 0xbfb8aa3b, v4
	v_exp_f32_e32 v4, v4
	v_exp_f32_e32 v0, v0
	v_exp_f32_e32 v1, v1
	v_mul_f32_e32 v2, 0xbfb8aa3b, v2
	v_add_f32_e32 v4, 1.0, v4
	v_rcp_f32_e32 v11, v4
	v_add_f32_e32 v4, v153, v6
	v_mul_f32_e32 v4, 0xbfb8aa3b, v4
	v_exp_f32_e32 v4, v4
	v_mul_f32_e32 v3, 0xbfb8aa3b, v3
	v_exp_f32_e32 v2, v2
	v_exp_f32_e32 v3, v3
	v_add_f32_e32 v4, 1.0, v4
	v_rcp_f32_e32 v6, v4
	v_add_f32_e32 v4, v153, v7
	v_add_f32_e32 v0, 1.0, v0
	v_add_f32_e32 v1, 1.0, v1
	v_mul_f32_e32 v4, 0xbfb8aa3b, v4
	v_rcp_f32_e32 v0, v0
	v_rcp_f32_e32 v1, v1
	v_add_f32_e32 v2, 1.0, v2
	v_add_f32_e32 v3, 1.0, v3
	v_exp_f32_e32 v4, v4
	v_rcp_f32_e32 v2, v2
	v_rcp_f32_e32 v3, v3
	v_pk_mul_f32 v[12:13], v[0:1], s[62:63] op_sel_hi:[1,0]
	v_add_f32_e32 v4, 1.0, v4
	v_rcp_f32_e32 v7, v4
	v_pk_mul_f32 v[14:15], v[2:3], s[62:63] op_sel_hi:[1,0]
	v_cvt_pk_bf16_f32 v4, v12, v13
	v_mad_u32_u24 v8, v50, s80, 0
	v_cvt_pk_bf16_f32 v5, v14, v15
	v_and_b32_e32 v51, 0xffff0000, v4
	v_lshlrev_b32_e32 v50, 16, v4
	v_pk_fma_f32 v[0:1], v[0:1], s[62:63], v[50:51] op_sel_hi:[1,0,1] neg_lo:[0,0,1] neg_hi:[0,0,1]
	v_and_b32_e32 v51, 0xffff0000, v5
	v_lshlrev_b32_e32 v50, 16, v5
	v_pk_fma_f32 v[2:3], v[2:3], s[62:63], v[50:51] op_sel_hi:[1,0,1] neg_lo:[0,0,1] neg_hi:[0,0,1]
	v_cvt_pk_bf16_f32 v50, v0, v1
	v_cvt_pk_bf16_f32 v51, v2, v3
	v_mfma_f32_16x16x16_bf16 v[0:3], v[72:73], v[4:5], 0
	v_add_u32_e32 v60, v8, v115
	v_add_u32_e32 v61, v60, v117
	v_add3_u32 v66, v8, v117, v115
	v_mfma_f32_16x16x16_bf16 v[2:5], v[72:73], v[50:51], v[0:3]
	v_add_u32_e32 v9, v8, v113
	v_add_u32_e32 v62, v9, v112
	v_lshl_add_u32 v63, v97, 2, v9
	s_nop 4
	v_sub_f32_e32 v0, v2, v12
	v_exp_f32_e32 v58, v2
	v_exp_f32_e64 v50, -v2
	v_exp_f32_e32 v59, v0
	v_exp_f32_e32 v67, v3
	v_exp_f32_e64 v51, -v3
	v_sub_f32_e32 v0, v3, v13
	v_and_b32_e32 v3, 0xffff0000, v165
	v_lshlrev_b32_e32 v2, 16, v165
	v_pk_mul_f32 v[54:55], v[76:77], v[2:3]
	v_exp_f32_e32 v68, v0
	v_pk_mul_f32 v[0:1], v[54:55], v[54:55]
	s_nop 1
	v_mov_b32_dpp v0, v0 quad_perm:[1,0,3,2] row_mask:0xf bank_mask:0xf bound_ctrl:1
	v_mov_b32_dpp v1, v1 quad_perm:[1,0,3,2] row_mask:0xf bank_mask:0xf bound_ctrl:1
	v_pk_fma_f32 v[0:1], v[54:55], v[54:55], v[0:1]
	s_nop 1
	v_mov_b32_dpp v12, v0 quad_perm:[2,3,0,1] row_mask:0xf bank_mask:0xf bound_ctrl:1
	v_mov_b32_dpp v13, v1 quad_perm:[2,3,0,1] row_mask:0xf bank_mask:0xf bound_ctrl:1
	v_pk_add_f32 v[0:1], v[0:1], v[12:13]
	s_nop 1
	v_mov_b32_dpp v12, v0 row_half_mirror row_mask:0xf bank_mask:0xf bound_ctrl:1
	v_mov_b32_dpp v13, v1 row_half_mirror row_mask:0xf bank_mask:0xf bound_ctrl:1
	v_pk_add_f32 v[0:1], v[0:1], v[12:13]
	s_nop 1
	v_mov_b32_dpp v12, v0 row_ror:8 row_mask:0xf bank_mask:0xf bound_ctrl:1
	v_mov_b32_dpp v13, v1 row_ror:8 row_mask:0xf bank_mask:0xf bound_ctrl:1
	v_pk_add_f32 v[12:13], v[0:1], v[12:13]
	v_mul_f32_e64 v0, v59, -v54
	v_cvt_pk_bf16_f32 v0, v0, s0
	ds_write_b16 v61, v0
	v_pk_mul_f32 v[0:1], v[54:55], v[10:11]
	v_pk_add_f32 v[10:11], v[10:11], -1.0 op_sel_hi:[1,0]
	v_pk_mul_f32 v[0:1], v[0:1], v[50:51]
; __device__ __forceinline__ float b2f(u16 b) { return __uint_as_float(((unsigned)b) << 16); }
; __device__ __forceinline__ void scan_pc(const Params& p, int j, const u16* R, const u16* K, const u16* V, u16* Y, u16* YB) {
;     ...
;       _Pragma("unroll") for (int jj = 0; jj < 4; ++jj) {
;         float ep = __builtin_amdgcn_exp2f(cum[jj]), em = __builtin_amdgcn_exp2f(-cum[jj]), ex = __builtin_amdgcn_exp2f(cum[jj] - lw[jj]);
;         float at = -kk[jj] * ex;
;         float rraw = b2f(q_.rr[jj]);
;         float rt = rraw * ep;
;         float kd = kv[jj] * (1.f + (ic[jj] - 1.f) * kac);
;         bt[jj] = kk[jj] * ic[jj] * em;
;         kt[jj] = kd * em;
;         int t = fq * 4 + jj, kc = w4 * 16 + fr;
;         float bsum = row_sum(rraw * kd * rkc);
;         reinterpret_cast<float*>(IMG + IMG_PL)[64 + w4 * 16 + t] = bsum;
;         IMG[(0 * 16 + t) * XT_LD + kc] = f2b(at);
;         IMG[(1 * 16 + t) * XT_LD + kc] = f2b(rt);
;         IMG[(2 * 16 + t) * XT_LD + kc] = f2b(bt[jj]);
;         IMG[(3 * 16 + t) * XT_LD + kc] = f2b(kt[jj]);
;         if (jj == 3) ep3 = ep;
;       }
;       if (fq == 3) reinterpret_cast<float*>(IMG + IMG_PL)[w4 * 16 + fr] = ep3;
;       *reinterpret_cast<s4*>(IMG + IMG_XK + (0 * 64 + w4 * 16 + fr) * XK_LD + fq * 4) = pack4(bt[0], bt[1], bt[2], bt[3]);
;       *reinterpret_cast<s4*>(IMG + IMG_XK + (1 * 64 + w4 * 16 + fr) * XK_LD + fq * 4) = pack4(kt[0], kt[1], kt[2], kt[3]);
;       s4 vp; _Pragma("unroll") for (int jj = 0; jj < 4; ++jj) vp[jj] = (short)q_.rv[jj];
;       *reinterpret_cast<s4*>(IMG + IMG_VT + (w4 * 16 + fr) * XK_LD + fq * 4) = vp;
	v_pk_fma_f32 v[10:11], v[74:75], v[10:11], 1.0 op_sel_hi:[1,1,0]
	v_cvt_pk_bf16_f32 v54, v0, s0
	v_pk_mul_f32 v[10:11], v[10:11], v[2:3]
	ds_write_b16 v66, v54 offset:4608
	v_pk_mul_f32 v[2:3], v[10:11], v[50:51]
	v_mul_f32_e64 v54, v68, -v55
	v_cvt_pk_bf16_f32 v50, v2, s0
	ds_write_b16 v66, v50 offset:6912
	v_lshlrev_b32_e32 v50, 16, v164
	v_and_b32_e32 v51, 0xffff0000, v164
	v_mul_f32_e32 v55, v58, v50
	v_cvt_pk_bf16_f32 v55, v55, s0
	v_pk_mul_f32 v[10:11], v[10:11], v[50:51]
	ds_write_b16 v66, v55 offset:2304
	v_mul_f32_e32 v55, v67, v51
	v_pk_mul_f32 v[50:51], v[78:79], v[10:11]
	v_exp_f32_e32 v66, v4
	s_nop 0
	v_mov_b32_dpp v50, v50 quad_perm:[1,0,3,2] row_mask:0xf bank_mask:0xf bound_ctrl:1
	v_mov_b32_dpp v51, v51 quad_perm:[1,0,3,2] row_mask:0xf bank_mask:0xf bound_ctrl:1
	v_pk_fma_f32 v[10:11], v[78:79], v[10:11], v[50:51]
	s_nop 1
	v_mov_b32_dpp v50, v10 quad_perm:[2,3,0,1] row_mask:0xf bank_mask:0xf bound_ctrl:1
	v_mov_b32_dpp v51, v11 quad_perm:[2,3,0,1] row_mask:0xf bank_mask:0xf bound_ctrl:1
	v_pk_add_f32 v[10:11], v[10:11], v[50:51]
	s_nop 1
	v_mov_b32_dpp v50, v10 row_half_mirror row_mask:0xf bank_mask:0xf bound_ctrl:1
	v_mov_b32_dpp v51, v11 row_half_mirror row_mask:0xf bank_mask:0xf bound_ctrl:1
	v_pk_add_f32 v[10:11], v[10:11], v[50:51]
	s_nop 1
	v_mov_b32_dpp v50, v10 row_ror:8 row_mask:0xf bank_mask:0xf bound_ctrl:1
	v_mov_b32_dpp v51, v11 row_ror:8 row_mask:0xf bank_mask:0xf bound_ctrl:1
	v_pk_add_f32 v[58:59], v[10:11], v[50:51]
	v_cvt_pk_bf16_f32 v10, v54, s0
	v_add_u32_e32 v11, v60, v120
	ds_write_b16 v11, v10
	v_cvt_pk_bf16_f32 v10, v55, s0
	v_add3_u32 v11, v8, v120, v115
	ds_write_b16 v11, v10 offset:2304
	v_cvt_pk_bf16_f32 v10, v1, s0
	v_exp_f32_e64 v50, -v4
	v_sub_f32_e32 v4, v4, v14
	v_and_b32_e32 v55, 0xffff0000, v163
	v_lshlrev_b32_e32 v54, 16, v163
	ds_write_b16 v11, v10 offset:4608
	v_cvt_pk_bf16_f32 v10, v3, s0
	v_exp_f32_e32 v67, v4
	v_sub_f32_e32 v4, v5, v15
	v_pk_mul_f32 v[60:61], v[76:77], v[54:55]
	ds_write_b16 v11, v10 offset:6912
	v_exp_f32_e32 v10, v5
	v_exp_f32_e64 v51, -v5
	v_exp_f32_e32 v68, v4
	v_pk_mul_f32 v[4:5], v[60:61], v[60:61]
	s_nop 1
	v_mov_b32_dpp v4, v4 quad_perm:[1,0,3,2] row_mask:0xf bank_mask:0xf bound_ctrl:1
	v_mov_b32_dpp v5, v5 quad_perm:[1,0,3,2] row_mask:0xf bank_mask:0xf bound_ctrl:1
	v_pk_fma_f32 v[4:5], v[60:61], v[60:61], v[4:5]
	s_nop 1
	v_mov_b32_dpp v14, v4 quad_perm:[2,3,0,1] row_mask:0xf bank_mask:0xf bound_ctrl:1
	v_mov_b32_dpp v15, v5 quad_perm:[2,3,0,1] row_mask:0xf bank_mask:0xf bound_ctrl:1
	v_pk_add_f32 v[4:5], v[4:5], v[14:15]
	s_nop 1
	v_mov_b32_dpp v14, v4 row_half_mirror row_mask:0xf bank_mask:0xf bound_ctrl:1
	v_mov_b32_dpp v15, v5 row_half_mirror row_mask:0xf bank_mask:0xf bound_ctrl:1
	v_pk_add_f32 v[4:5], v[4:5], v[14:15]
	s_nop 1
	v_mov_b32_dpp v14, v4 row_ror:8 row_mask:0xf bank_mask:0xf bound_ctrl:1
	v_mov_b32_dpp v15, v5 row_ror:8 row_mask:0xf bank_mask:0xf bound_ctrl:1
	v_pk_add_f32 v[14:15], v[4:5], v[14:15]
	v_mul_f32_e64 v4, v67, -v60
	v_cvt_pk_bf16_f32 v4, v4, s0
	ds_write_b16 v11, v4 offset:144
	v_pk_mul_f32 v[4:5], v[60:61], v[6:7]
	v_pk_add_f32 v[6:7], v[6:7], -1.0 op_sel_hi:[1,0]
	v_pk_mul_f32 v[4:5], v[4:5], v[50:51]
	ds_write_b128 v62, v[12:15] offset:17408
	v_cvt_pk_bf16_f32 v12, v4, s0
	v_pk_fma_f32 v[6:7], v[74:75], v[6:7], 1.0 op_sel_hi:[1,1,0]
	ds_write_b16 v11, v12 offset:4752
	v_pk_mul_f32 v[12:13], v[6:7], v[54:55]
	v_and_b32_e32 v15, 0xffff0000, v162
	v_pk_mul_f32 v[6:7], v[12:13], v[50:51]
	v_mul_f32_e64 v62, v68, -v61
	v_cvt_pk_bf16_f32 v14, v6, s0
	ds_write_b16 v11, v14 offset:7056
	v_lshlrev_b32_e32 v14, 16, v162
	v_mul_f32_e32 v50, v66, v14
	v_cvt_pk_bf16_f32 v50, v50, s0
	v_pk_mul_f32 v[12:13], v[12:13], v[14:15]
	ds_write_b16 v11, v50 offset:2448
	v_mul_f32_e32 v50, v10, v15
	v_pk_mul_f32 v[14:15], v[78:79], v[12:13]
	s_nop 1
	v_mov_b32_dpp v14, v14 quad_perm:[1,0,3,2] row_mask:0xf bank_mask:0xf bound_ctrl:1
	v_mov_b32_dpp v15, v15 quad_perm:[1,0,3,2] row_mask:0xf bank_mask:0xf bound_ctrl:1
	v_pk_fma_f32 v[12:13], v[78:79], v[12:13], v[14:15]
	s_nop 1
	v_mov_b32_dpp v14, v12 quad_perm:[2,3,0,1] row_mask:0xf bank_mask:0xf bound_ctrl:1
	v_mov_b32_dpp v15, v13 quad_perm:[2,3,0,1] row_mask:0xf bank_mask:0xf bound_ctrl:1
	v_pk_add_f32 v[12:13], v[12:13], v[14:15]
	s_nop 1
	v_mov_b32_dpp v14, v12 row_half_mirror row_mask:0xf bank_mask:0xf bound_ctrl:1
	v_mov_b32_dpp v15, v13 row_half_mirror row_mask:0xf bank_mask:0xf bound_ctrl:1
	v_pk_add_f32 v[12:13], v[12:13], v[14:15]
	s_nop 1
	v_mov_b32_dpp v14, v12 row_ror:8 row_mask:0xf bank_mask:0xf bound_ctrl:1
	v_mov_b32_dpp v15, v13 row_ror:8 row_mask:0xf bank_mask:0xf bound_ctrl:1
	v_pk_add_f32 v[60:61], v[12:13], v[14:15]
	v_cvt_pk_bf16_f32 v12, v62, s0
	ds_write_b16 v11, v12 offset:288
	v_cvt_pk_bf16_f32 v12, v50, s0
	ds_write_b16 v11, v12 offset:2592
	v_cvt_pk_bf16_f32 v12, v5, s0
	ds_write_b16 v11, v12 offset:4896
	v_cvt_pk_bf16_f32 v12, v7, s0
	ds_write_b128 v63, v[58:61] offset:17152
	ds_write_b16 v11, v12 offset:7200
	s_and_saveexec_b64 s[62:63], s[12:13]
	s_cbranch_execz .LBB0_2717
	v_lshl_add_u32 v9, v96, 2, v9
	ds_write_b32 v9, v10 offset:16896
	s_branch .LBB0_2717
